# v62 + attention loop bookkeeping moved ahead of the per-step barrier
# baseline (speedup 1.0000x reference)
;   #define RESC() do{ if(resc){ asm volatile("s_waitcnt lgkmcnt(0)":::"memory"); \
;       _Pragma("unroll") for(int d_=0;d_<2;++d_) _Pragma("unroll") for(int r=0;r<16;++r)o[d_][r]*=wsf[crow(r,hi)]; } }while(0)
;   #define ROT() do{sl_prev=sl_cur;sl_cur=sl_next;sl_next=(sl_next==(NSLOT-1)*SLOTB)?0:sl_next+SLOTB;}while(0)
;   #define WAIT_STEADY() WAIT_BAR(3)
;   #define WAIT_STEADY() WAIT_BAR(2)
; template<int THRL,bool NOMAX> __device__ __forceinline__ void attn_unit(int b,int h,int qb,int t0,const bf16*Q,const bf16*__restrict__ KV,const bf16*__restrict__ GA,bf16*O,char*shm){
;     ...
;   for(;t+5<NT;t+=2){
;     STEP(pB0,pB1,pA0,pA1,t,true,true,true);     WAIT_STEADY(); RESC(); ROT();
.LBB0_479:
	v_add_u32_e32 v179, s16, v2
	ds_read_b64_tr_b16 v[198:199], v179 offset:24576
	ds_read_b64_tr_b16 v[200:201], v179 offset:25088
	v_add_f32_e32 v88, v68, v69
	v_add_f32_e32 v88, v70, v88
	v_add_f32_e32 v88, v71, v88
	v_add_f32_e32 v88, v72, v88
	v_add_f32_e32 v88, v73, v88
	v_cvt_pk_bf16_f32 v160, v68, v69
	v_cvt_pk_bf16_f32 v161, v70, v71
	v_mfma_f32_32x32x16_bf16 v[100:115], v[84:87], v[152:155], v[36:51]
	ds_read_b64_tr_b16 v[202:203], v179 offset:28672
	ds_read_b64_tr_b16 v[204:205], v179 offset:29184
	v_add_f32_e32 v68, v74, v88
	v_mfma_f32_32x32x16_bf16 v[84:99], v[168:171], v[152:155], v[36:51]
	v_add_f32_e32 v68, v75, v68
	v_add_f32_e32 v68, v76, v68
	v_add_f32_e32 v140, v77, v68
	v_cvt_pk_bf16_f32 v162, v72, v73
	v_cvt_pk_bf16_f32 v163, v74, v75
	ds_read_b64_tr_b16 v[68:69], v179 offset:25600
	ds_read_b64_tr_b16 v[70:71], v179 offset:26112
	v_add_f32_e32 v72, v78, v140
	v_add_f32_e32 v72, v79, v72
	v_add_f32_e32 v72, v80, v72
	v_add_f32_e32 v140, v81, v72
	v_cvt_pk_bf16_f32 v156, v76, v77
	v_cvt_pk_bf16_f32 v157, v78, v79
	v_mfma_f32_32x32x16_bf16 v[100:115], v[172:175], v[144:147], v[100:115]
	ds_read_b64_tr_b16 v[72:73], v179 offset:29696
	ds_read_b64_tr_b16 v[74:75], v179 offset:30208
	v_mfma_f32_32x32x16_bf16 v[84:99], v[164:167], v[144:147], v[84:99]
	v_add_f32_e32 v76, v82, v140
	v_add_f32_e32 v76, v83, v76
	v_add_f32_e32 v76, v52, v76
	v_add_f32_e32 v140, v53, v76
	v_cvt_pk_bf16_f32 v158, v80, v81
	v_cvt_pk_bf16_f32 v159, v82, v83
	ds_read_b64_tr_b16 v[76:77], v179 offset:26624
	ds_read_b64_tr_b16 v[78:79], v179 offset:27136
	v_add_f32_e32 v80, v54, v140
	v_add_f32_e32 v80, v55, v80
	v_add_f32_e32 v80, v56, v80
	v_add_f32_e32 v80, v57, v80
	v_cvt_pk_bf16_f32 v148, v52, v53
	v_cvt_pk_bf16_f32 v149, v54, v55
	v_mfma_f32_32x32x16_bf16 v[100:115], v[128:131], v[136:139], v[100:115]
	ds_read_b64_tr_b16 v[52:53], v179 offset:30720
	ds_read_b64_tr_b16 v[54:55], v179 offset:31232
	v_mfma_f32_32x32x16_bf16 v[84:99], v[124:127], v[136:139], v[84:99]
	v_add_f32_e32 v80, v58, v80
	v_add_f32_e32 v80, v59, v80
	v_add_f32_e32 v80, v60, v80
	v_add_f32_e32 v80, v61, v80
	v_cvt_pk_bf16_f32 v150, v56, v57
	v_cvt_pk_bf16_f32 v151, v58, v59
	ds_read_b64_tr_b16 v[56:57], v179 offset:27648
	ds_read_b64_tr_b16 v[58:59], v179 offset:28160
	v_add_f32_e32 v80, v62, v80
	v_add_f32_e32 v80, v63, v80
	v_add_f32_e32 v80, v64, v80
	v_add_f32_e32 v80, v65, v80
	v_cvt_pk_bf16_f32 v140, v60, v61
	v_cvt_pk_bf16_f32 v141, v62, v63
	v_mfma_f32_32x32x16_bf16 v[100:115], v[120:123], v[132:135], v[100:115]
	ds_read_b64_tr_b16 v[60:61], v179 offset:31744
	ds_read_b64_tr_b16 v[62:63], v179 offset:32256
	v_mfma_f32_32x32x16_bf16 v[84:99], v[116:119], v[132:135], v[84:99]
	v_add_f32_e32 v80, v66, v80
	v_add_f32_e32 v80, v67, v80
	v_add_f32_e32 v179, 0, v80
	v_cvt_pk_bf16_f32 v142, v64, v65
	v_cvt_pk_bf16_f32 v143, v66, v67
	s_add_i32 s16, s21, 0x4000
	s_and_b32 s16, s16, 0xfc000
	s_lshl_b32 s16, s16, 1
	v_lshl_add_u64 v[218:219], v[182:183], 0, s[16:17]
	s_add_i32 m0, s22, s9
	s_nop 0
	global_load_lds_dwordx4 v[218:219], off
	s_waitcnt lgkmcnt(4)
	v_mfma_f32_32x32x16_bf16 v[4:19], v[160:163], v[198:201], v[4:19]
	v_exp_f32_e32 v100, v100
	v_exp_f32_e32 v101, v101
	v_exp_f32_e32 v102, v102
	v_exp_f32_e32 v103, v103
	v_mfma_f32_32x32x16_bf16 v[20:35], v[160:163], v[202:205], v[20:35]
	v_exp_f32_e32 v104, v104
	v_exp_f32_e32 v105, v105
	v_exp_f32_e32 v106, v106
	v_exp_f32_e32 v107, v107
	v_add_u32_e32 v80, s15, v189
	ds_read_b128 v[64:67], v80
	ds_read_b128 v[120:123], v80 offset:512
	v_mfma_f32_32x32x16_bf16 v[4:19], v[156:159], v[68:71], v[4:19]
	v_exp_f32_e32 v108, v108
	v_exp_f32_e32 v109, v109
	v_exp_f32_e32 v110, v110
	v_exp_f32_e32 v111, v111
	ds_read_b128 v[124:127], v80 offset:2048
	ds_read_b128 v[128:131], v80 offset:2560
	v_mfma_f32_32x32x16_bf16 v[20:35], v[156:159], v[72:75], v[20:35]
	v_exp_f32_e32 v112, v112
	v_exp_f32_e32 v113, v113
	v_exp_f32_e32 v114, v114
	v_exp_f32_e32 v115, v115
	ds_read_b128 v[164:167], v80 offset:4096
	ds_read_b128 v[168:171], v80 offset:4608
	v_mfma_f32_32x32x16_bf16 v[4:19], v[148:151], v[76:79], v[4:19]
	v_exp_f32_e32 v84, v84
	v_exp_f32_e32 v85, v85
	v_exp_f32_e32 v86, v86
	v_exp_f32_e32 v87, v87
	ds_read_b128 v[172:175], v80 offset:6144
	ds_read_b128 v[116:119], v80 offset:6656
	v_mfma_f32_32x32x16_bf16 v[20:35], v[148:151], v[52:55], v[20:35]
	v_exp_f32_e32 v88, v88
	v_exp_f32_e32 v89, v89
	v_exp_f32_e32 v90, v90
	v_exp_f32_e32 v91, v91
	s_waitcnt lgkmcnt(8)
	v_mfma_f32_32x32x16_bf16 v[4:19], v[140:143], v[56:59], v[4:19]
	v_exp_f32_e32 v92, v92
	v_exp_f32_e32 v93, v93
	v_exp_f32_e32 v94, v94
	v_exp_f32_e32 v95, v95
	v_mfma_f32_32x32x16_bf16 v[20:35], v[140:143], v[60:63], v[20:35]
	v_exp_f32_e32 v96, v96
	v_exp_f32_e32 v97, v97
	v_exp_f32_e32 v98, v98
	v_exp_f32_e32 v99, v99
	s_add_i32 s16, s20, 0xffff4000
	s_and_b32 s16, s16, 0xfc000
	s_lshl_b32 s16, s16, 1
	v_lshl_add_u64 v[218:219], v[180:181], 0, s[16:17]
	s_add_i32 m0, s15, s8
	s_nop 0
	global_load_lds_dwordx4 v[218:219], off
	s_add_i32 s16, s15, 0x2000
	s_cmpk_lg_i32 s15, 0x4000
	s_cselect_b32 s23, s16, 0
	v_add_u32_e32 v190, s22, v2
	s_waitcnt vmcnt(2) lgkmcnt(0)
	s_barrier
;   #define RESC() do{ if(resc){ asm volatile("s_waitcnt lgkmcnt(0)":::"memory"); \
;       _Pragma("unroll") for(int d_=0;d_<2;++d_) _Pragma("unroll") for(int r=0;r<16;++r)o[d_][r]*=wsf[crow(r,hi)]; } }while(0)
;   #define ROT() do{sl_prev=sl_cur;sl_cur=sl_next;sl_next=(sl_next==(NSLOT-1)*SLOTB)?0:sl_next+SLOTB;}while(0)
;   #define WAIT_STEADY() WAIT_BAR(3)
;   #define WAIT_STEADY() WAIT_BAR(2)
; template<int THRL,bool NOMAX> __device__ __forceinline__ void attn_unit(int b,int h,int qb,int t0,const bf16*Q,const bf16*__restrict__ KV,const bf16*__restrict__ GA,bf16*O,char*shm){
;     ...
;   for(;t+5<NT;t+=2){
;     STEP(pB0,pB1,pA0,pA1,t,true,true,true);     WAIT_STEADY(); RESC(); ROT();
;     STEP(pA0,pA1,pB0,pB1,t+1,true,true,true);   WAIT_STEADY(); RESC(); ROT();
;   }
	ds_read_b64_tr_b16 v[198:199], v190 offset:24576
	ds_read_b64_tr_b16 v[200:201], v190 offset:25088
	v_mfma_f32_32x32x16_bf16 v[68:83], v[64:67], v[152:155], v[36:51]
	v_add_f32_e32 v52, v100, v101
	v_add_f32_e32 v52, v102, v52
	v_add_f32_e32 v52, v103, v52
	v_add_f32_e32 v52, v104, v52
	v_add_f32_e32 v52, v105, v52
	v_cvt_pk_bf16_f32 v160, v100, v101
	v_cvt_pk_bf16_f32 v161, v102, v103
	ds_read_b64_tr_b16 v[202:203], v190 offset:28672
	ds_read_b64_tr_b16 v[204:205], v190 offset:29184
	v_add_f32_e32 v52, v106, v52
	v_add_f32_e32 v52, v107, v52
	v_add_f32_e32 v52, v108, v52
	v_add_f32_e32 v140, v109, v52
	v_mfma_f32_32x32x16_bf16 v[52:67], v[120:123], v[152:155], v[36:51]
	v_cvt_pk_bf16_f32 v162, v104, v105
	v_cvt_pk_bf16_f32 v163, v106, v107
	ds_read_b64_tr_b16 v[100:101], v190 offset:25600
	ds_read_b64_tr_b16 v[102:103], v190 offset:26112
	v_mfma_f32_32x32x16_bf16 v[68:83], v[124:127], v[144:147], v[68:83]
	v_add_f32_e32 v104, v110, v140
	v_add_f32_e32 v104, v111, v104
	v_add_f32_e32 v104, v112, v104
	v_add_f32_e32 v120, v113, v104
	v_cvt_pk_bf16_f32 v156, v108, v109
	v_cvt_pk_bf16_f32 v157, v110, v111
	ds_read_b64_tr_b16 v[104:105], v190 offset:29696
	ds_read_b64_tr_b16 v[106:107], v190 offset:30208
	v_mfma_f32_32x32x16_bf16 v[52:67], v[128:131], v[144:147], v[52:67]
	v_add_f32_e32 v108, v114, v120
	v_add_f32_e32 v108, v115, v108
	v_add_f32_e32 v108, v84, v108
	v_add_f32_e32 v120, v85, v108
	v_cvt_pk_bf16_f32 v158, v112, v113
	v_cvt_pk_bf16_f32 v159, v114, v115
	ds_read_b64_tr_b16 v[108:109], v190 offset:26624
	ds_read_b64_tr_b16 v[110:111], v190 offset:27136
	v_mfma_f32_32x32x16_bf16 v[68:83], v[164:167], v[136:139], v[68:83]
	v_add_f32_e32 v112, v86, v120
	v_add_f32_e32 v112, v87, v112
	v_add_f32_e32 v112, v88, v112
	v_add_f32_e32 v120, v89, v112
	v_cvt_pk_bf16_f32 v148, v84, v85
	v_cvt_pk_bf16_f32 v149, v86, v87
	ds_read_b64_tr_b16 v[112:113], v190 offset:30720
	ds_read_b64_tr_b16 v[114:115], v190 offset:31232
	v_mfma_f32_32x32x16_bf16 v[52:67], v[168:171], v[136:139], v[52:67]
	v_add_f32_e32 v84, v90, v120
	v_add_f32_e32 v84, v91, v84
	v_add_f32_e32 v84, v92, v84
	v_add_f32_e32 v84, v93, v84
	v_cvt_pk_bf16_f32 v150, v88, v89
	v_cvt_pk_bf16_f32 v151, v90, v91
	ds_read_b64_tr_b16 v[88:89], v190 offset:27648
	ds_read_b64_tr_b16 v[90:91], v190 offset:28160
	v_mfma_f32_32x32x16_bf16 v[68:83], v[172:175], v[132:135], v[68:83]
	v_add_f32_e32 v84, v94, v84
	v_add_f32_e32 v84, v95, v84
	v_add_f32_e32 v84, v96, v84
	v_add_f32_e32 v84, v97, v84
	v_cvt_pk_bf16_f32 v140, v92, v93
	v_cvt_pk_bf16_f32 v141, v94, v95
	ds_read_b64_tr_b16 v[92:93], v190 offset:31744
	ds_read_b64_tr_b16 v[94:95], v190 offset:32256
	v_mfma_f32_32x32x16_bf16 v[52:67], v[116:119], v[132:135], v[52:67]
	v_add_f32_e32 v84, v98, v84
	v_add_f32_e32 v84, v99, v84
	v_add_f32_e32 v190, 0, v84
	v_cvt_pk_bf16_f32 v142, v96, v97
	v_cvt_pk_bf16_f32 v143, v98, v99
	s_and_b32 s16, s20, 0xfc000
	s_lshl_b32 s16, s16, 1
	v_lshl_add_u64 v[218:219], v[182:183], 0, s[16:17]
	s_add_i32 m0, s15, s9
	s_nop 0
	global_load_lds_dwordx4 v[218:219], off
	s_waitcnt lgkmcnt(4)
	v_mfma_f32_32x32x16_bf16 v[4:19], v[160:163], v[198:201], v[4:19]
	v_exp_f32_e32 v68, v68
	v_exp_f32_e32 v69, v69
	v_exp_f32_e32 v70, v70
	v_exp_f32_e32 v71, v71
	v_mfma_f32_32x32x16_bf16 v[20:35], v[160:163], v[202:205], v[20:35]
	v_exp_f32_e32 v72, v72
	v_exp_f32_e32 v73, v73
	v_exp_f32_e32 v74, v74
	v_exp_f32_e32 v75, v75
	v_add_u32_e32 v96, s23, v189
	ds_read_b128 v[84:87], v96
	ds_read_b128 v[168:171], v96 offset:512
	v_mfma_f32_32x32x16_bf16 v[4:19], v[156:159], v[100:103], v[4:19]
	v_exp_f32_e32 v76, v76
	v_exp_f32_e32 v77, v77
	v_exp_f32_e32 v78, v78
	v_exp_f32_e32 v79, v79
	ds_read_b128 v[172:175], v96 offset:2048
	ds_read_b128 v[164:167], v96 offset:2560
	v_mfma_f32_32x32x16_bf16 v[20:35], v[156:159], v[104:107], v[20:35]
	v_exp_f32_e32 v80, v80
	v_exp_f32_e32 v81, v81
	v_exp_f32_e32 v82, v82
	v_exp_f32_e32 v83, v83
	ds_read_b128 v[128:131], v96 offset:4096
	ds_read_b128 v[124:127], v96 offset:4608
	v_mfma_f32_32x32x16_bf16 v[4:19], v[148:151], v[108:111], v[4:19]
	v_exp_f32_e32 v52, v52
	v_exp_f32_e32 v53, v53
	v_exp_f32_e32 v54, v54
	v_exp_f32_e32 v55, v55
	ds_read_b128 v[120:123], v96 offset:6144
	ds_read_b128 v[116:119], v96 offset:6656
	v_mfma_f32_32x32x16_bf16 v[20:35], v[148:151], v[112:115], v[20:35]
	v_exp_f32_e32 v56, v56
	v_exp_f32_e32 v57, v57
	v_exp_f32_e32 v58, v58
	v_exp_f32_e32 v59, v59
	s_waitcnt lgkmcnt(8)
	v_mfma_f32_32x32x16_bf16 v[4:19], v[140:143], v[88:91], v[4:19]
	v_exp_f32_e32 v60, v60
	v_exp_f32_e32 v61, v61
	v_exp_f32_e32 v62, v62
	v_exp_f32_e32 v63, v63
	v_mfma_f32_32x32x16_bf16 v[20:35], v[140:143], v[92:95], v[20:35]
	v_exp_f32_e32 v64, v64
	v_exp_f32_e32 v65, v65
	v_exp_f32_e32 v66, v66
	v_exp_f32_e32 v67, v67
	s_add_i32 s26, s23, 0x2000
	s_and_b32 s16, s21, 0xfc000
	s_lshl_b32 s16, s16, 1
	v_lshl_add_u64 v[218:219], v[180:181], 0, s[16:17]
	s_add_i32 m0, s23, s8
	s_nop 0
	global_load_lds_dwordx4 v[218:219], off
	s_cmpk_lg_i32 s23, 0x4000
	v_add_f32_e32 v88, v191, v179
	s_mov_b32 s16, s15
	s_cselect_b32 s15, s26, 0
	s_add_i32 s14, s14, 2
	s_add_i32 s21, s21, 0x8000
	s_add_i32 s20, s20, 0x8000
	s_mov_b32 s22, s23
	v_add_f32_e32 v191, v88, v190
	s_cmp_gt_u32 s14, 56
	s_waitcnt vmcnt(2) lgkmcnt(0)
	s_barrier
	s_cbranch_scc0 .LBB0_479
;   #define RESC() do{ if(resc){ asm volatile("s_waitcnt lgkmcnt(0)":::"memory"); \
;       _Pragma("unroll") for(int d_=0;d_<2;++d_) _Pragma("unroll") for(int r=0;r<16;++r)o[d_][r]*=wsf[crow(r,hi)]; } }while(0)
;   #define ROT() do{sl_prev=sl_cur;sl_cur=sl_next;sl_next=(sl_next==(NSLOT-1)*SLOTB)?0:sl_next+SLOTB;}while(0)
;   #define ENDW(tt) do{ if((tt)+3<NT){WAIT_BAR(2);} else if((tt)+2<NT){WAIT_BAR(1);} else {WAIT_BAR(0);} }while(0)
; template<int THRL,bool NOMAX> __device__ __forceinline__ void attn_unit(int b,int h,int qb,int t0,const bf16*Q,const bf16*__restrict__ KV,const bf16*__restrict__ GA,bf16*O,char*shm){
;     ...
;   for(;t+1<NT;t+=2){
;     STEP(pB0,pB1,pA0,pA1,t,(t+3<NT),(t+1<NT),(t+1<NT));       ENDW(t);   RESC(); ROT();
	s_and_b32 s12, s12, 0x3fffffc0
	s_cmp_lg_u32 0, -1
	s_cselect_b32 s14, 0, 0
	s_add_i32 s15, s14, 0x6000
	s_lshl_b32 s12, s12, 2
	v_add_u32_e32 v88, s15, v177
	s_add_i32 s12, s12, 0
	v_add3_u32 v190, v88, v176, v178
	ds_read_b64_tr_b16 v[198:199], v2 offset:32768
	ds_read_b64_tr_b16 v[200:201], v2 offset:33280
	v_add_f32_e32 v88, v68, v69
	v_add_f32_e32 v88, v70, v88
	v_add_f32_e32 v88, v71, v88
	v_add_f32_e32 v88, v72, v88
	v_add_f32_e32 v88, v73, v88
	v_cvt_pk_bf16_f32 v160, v68, v69
	v_cvt_pk_bf16_f32 v161, v70, v71
	s_waitcnt lgkmcnt(9)
	v_mfma_f32_32x32x16_bf16 v[100:115], v[84:87], v[152:155], v[36:51]
	ds_read_b64_tr_b16 v[176:177], v2 offset:36864
	ds_read_b64_tr_b16 v[178:179], v2 offset:37376
	v_add_f32_e32 v68, v74, v88
	v_add_f32_e32 v68, v75, v68
	v_add_f32_e32 v68, v76, v68
	v_add_f32_e32 v140, v77, v68
	v_cvt_pk_bf16_f32 v162, v72, v73
	v_cvt_pk_bf16_f32 v163, v74, v75
	s_waitcnt lgkmcnt(10)
	v_mfma_f32_32x32x16_bf16 v[84:99], v[168:171], v[152:155], v[36:51]
	ds_read_b64_tr_b16 v[68:69], v2 offset:33792
	ds_read_b64_tr_b16 v[70:71], v2 offset:34304
	v_add_f32_e32 v72, v78, v140
	v_add_f32_e32 v72, v79, v72
	v_add_f32_e32 v72, v80, v72
	v_add_f32_e32 v140, v81, v72
	v_cvt_pk_bf16_f32 v156, v76, v77
	v_cvt_pk_bf16_f32 v157, v78, v79
	s_waitcnt lgkmcnt(11)
	v_mfma_f32_32x32x16_bf16 v[100:115], v[172:175], v[144:147], v[100:115]
	ds_read_b64_tr_b16 v[72:73], v2 offset:37888
	ds_read_b64_tr_b16 v[74:75], v2 offset:38400
	v_add_f32_e32 v76, v82, v140
	v_add_f32_e32 v76, v83, v76
	v_add_f32_e32 v76, v52, v76
	v_add_f32_e32 v140, v53, v76
	v_cvt_pk_bf16_f32 v158, v80, v81
	v_cvt_pk_bf16_f32 v159, v82, v83
	s_waitcnt lgkmcnt(12)
	v_mfma_f32_32x32x16_bf16 v[84:99], v[164:167], v[144:147], v[84:99]
	ds_read_b64_tr_b16 v[76:77], v2 offset:34816
	ds_read_b64_tr_b16 v[78:79], v2 offset:35328
	v_add_f32_e32 v80, v54, v140
	v_add_f32_e32 v80, v55, v80
	v_add_f32_e32 v80, v56, v80
	v_add_f32_e32 v80, v57, v80
	v_cvt_pk_bf16_f32 v148, v52, v53
	v_cvt_pk_bf16_f32 v149, v54, v55
	s_waitcnt lgkmcnt(13)
	v_mfma_f32_32x32x16_bf16 v[100:115], v[128:131], v[136:139], v[100:115]
	ds_read_b64_tr_b16 v[52:53], v2 offset:38912
	ds_read_b64_tr_b16 v[54:55], v2 offset:39424
	v_add_f32_e32 v80, v58, v80
	v_add_f32_e32 v80, v59, v80
	v_add_f32_e32 v80, v60, v80
	v_add_f32_e32 v80, v61, v80
	v_cvt_pk_bf16_f32 v150, v56, v57
	v_cvt_pk_bf16_f32 v151, v58, v59
	s_waitcnt lgkmcnt(14)
	v_mfma_f32_32x32x16_bf16 v[84:99], v[124:127], v[136:139], v[84:99]
	ds_read_b64_tr_b16 v[56:57], v2 offset:35840
	ds_read_b64_tr_b16 v[58:59], v2 offset:36352
	v_add_f32_e32 v80, v62, v80
	v_add_f32_e32 v80, v63, v80
	v_add_f32_e32 v80, v64, v80
	v_add_f32_e32 v80, v65, v80
	v_cvt_pk_bf16_f32 v140, v60, v61
	v_cvt_pk_bf16_f32 v141, v62, v63
	s_waitcnt lgkmcnt(14)
	v_mfma_f32_32x32x16_bf16 v[100:115], v[120:123], v[132:135], v[100:115]
	ds_read_b64_tr_b16 v[60:61], v2 offset:39936
	ds_read_b64_tr_b16 v[62:63], v2 offset:40448
	v_add_f32_e32 v80, v66, v80
	v_add_f32_e32 v80, v67, v80
	v_add_f32_e32 v80, 0, v80
	v_cvt_pk_bf16_f32 v142, v64, v65
	v_cvt_pk_bf16_f32 v143, v66, v67
	v_mfma_f32_32x32x16_bf16 v[84:99], v[116:119], v[132:135], v[84:99]
	v_readlane_b32 s20, v254, 56
	v_readlane_b32 s21, v254, 57
	s_mov_b32 s21, s17
	s_add_i32 s13, s14, s13
	v_lshl_add_u64 v[64:65], v[182:183], 0, s[20:21]
	s_add_i32 s14, s13, 0x4000
	s_mov_b32 s15, m0
	s_mov_b32 m0, s14
	s_nop 0
	global_load_lds_dwordx4 v[64:65], off
	s_mov_b32 m0, s15
	v_add_f32_e32 v191, v191, v80
	v_readlane_b32 s14, v254, 58
	v_readlane_b32 s15, v254, 59
	s_mov_b32 s15, s17
	s_mov_b32 s16, s14
	v_lshl_add_u64 v[64:65], v[180:181], 0, s[14:15]
	s_mov_b32 s14, m0
	s_mov_b32 m0, s8
	s_nop 0
	global_load_lds_dwordx4 v[64:65], off
	s_mov_b32 m0, s14
	v_writelane_b32 v254, s16, 58
	s_nop 1
	v_writelane_b32 v254, s17, 59
	s_waitcnt lgkmcnt(14)
	v_mfma_f32_32x32x16_bf16 v[4:19], v[160:163], v[198:201], v[4:19]
	v_exp_f32_e32 v100, v100
	v_exp_f32_e32 v101, v101
	v_exp_f32_e32 v102, v102
	v_exp_f32_e32 v103, v103
	s_waitcnt lgkmcnt(12)
	v_mfma_f32_32x32x16_bf16 v[20:35], v[160:163], v[176:179], v[20:35]
	v_exp_f32_e32 v104, v104
	v_exp_f32_e32 v105, v105
	v_exp_f32_e32 v106, v106
	v_exp_f32_e32 v107, v107
	ds_read_b128 v[64:67], v189
	ds_read_b128 v[80:83], v189 offset:512
	s_waitcnt lgkmcnt(12)
	v_mfma_f32_32x32x16_bf16 v[4:19], v[156:159], v[68:71], v[4:19]
	v_exp_f32_e32 v108, v108
	v_exp_f32_e32 v109, v109
	v_exp_f32_e32 v110, v110
	v_exp_f32_e32 v111, v111
	ds_read_b128 v[164:167], v189 offset:2048
	ds_read_b128 v[168:171], v189 offset:2560
	s_waitcnt lgkmcnt(12)
	v_mfma_f32_32x32x16_bf16 v[20:35], v[156:159], v[72:75], v[20:35]
	v_exp_f32_e32 v112, v112
	v_exp_f32_e32 v113, v113
	v_exp_f32_e32 v114, v114
	v_exp_f32_e32 v115, v115
	ds_read_b128 v[172:175], v189 offset:4096
	ds_read_b128 v[176:179], v189 offset:4608
	s_waitcnt lgkmcnt(12)
	v_mfma_f32_32x32x16_bf16 v[4:19], v[148:151], v[76:79], v[4:19]
	v_exp_f32_e32 v84, v84
	v_exp_f32_e32 v85, v85
	v_exp_f32_e32 v86, v86
	v_exp_f32_e32 v87, v87
	ds_read_b128 v[198:201], v189 offset:6144
	ds_read_b128 v[72:75], v189 offset:6656
	s_waitcnt lgkmcnt(12)
	v_mfma_f32_32x32x16_bf16 v[20:35], v[148:151], v[52:55], v[20:35]
	v_exp_f32_e32 v88, v88
	v_exp_f32_e32 v89, v89
	v_exp_f32_e32 v90, v90
	v_exp_f32_e32 v91, v91
	s_waitcnt lgkmcnt(10)
	v_mfma_f32_32x32x16_bf16 v[4:19], v[140:143], v[56:59], v[4:19]
	v_exp_f32_e32 v92, v92
	v_exp_f32_e32 v93, v93
	v_exp_f32_e32 v94, v94
	v_exp_f32_e32 v95, v95
	s_waitcnt lgkmcnt(8)
	v_mfma_f32_32x32x16_bf16 v[20:35], v[140:143], v[60:63], v[20:35]
	v_exp_f32_e32 v96, v96
	v_exp_f32_e32 v97, v97
	v_exp_f32_e32 v98, v98
	v_exp_f32_e32 v99, v99
	s_waitcnt vmcnt(2) lgkmcnt(0)
	s_barrier
;   #define RESC() do{ if(resc){ asm volatile("s_waitcnt lgkmcnt(0)":::"memory"); \
;       _Pragma("unroll") for(int d_=0;d_<2;++d_) _Pragma("unroll") for(int r=0;r<16;++r)o[d_][r]*=wsf[crow(r,hi)]; } }while(0)
;   #define ROT() do{sl_prev=sl_cur;sl_cur=sl_next;sl_next=(sl_next==(NSLOT-1)*SLOTB)?0:sl_next+SLOTB;}while(0)
;   #define ENDW(tt) do{ if((tt)+3<NT){WAIT_BAR(2);} else if((tt)+2<NT){WAIT_BAR(1);} else {WAIT_BAR(0);} }while(0)
; template<int THRL,bool NOMAX> __device__ __forceinline__ void attn_unit(int b,int h,int qb,int t0,const bf16*Q,const bf16*__restrict__ KV,const bf16*__restrict__ GA,bf16*O,char*shm){
;     ...
;   for(;t+1<NT;t+=2){
;     STEP(pB0,pB1,pA0,pA1,t,(t+3<NT),(t+1<NT),(t+1<NT));       ENDW(t);   RESC(); ROT();
;     STEP(pA0,pA1,pB0,pB1,t+1,(t+4<NT),(t+2<NT),(t+2<NT));     ENDW(t+1); RESC(); ROT();
	ds_read_b64_tr_b16 v[202:203], v2 offset:40960
	ds_read_b64_tr_b16 v[204:205], v2 offset:41472
	v_add_f32_e32 v52, v100, v101
	v_add_f32_e32 v52, v102, v52
	v_add_f32_e32 v52, v103, v52
	v_add_f32_e32 v52, v104, v52
	v_add_f32_e32 v52, v105, v52
	v_cvt_pk_bf16_f32 v160, v100, v101
	v_cvt_pk_bf16_f32 v161, v102, v103
	s_waitcnt lgkmcnt(9)
	v_mfma_f32_32x32x16_bf16 v[116:131], v[64:67], v[152:155], v[36:51]
	ds_read_b64_tr_b16 v[100:101], v2 offset:45056
	ds_read_b64_tr_b16 v[102:103], v2 offset:45568
	v_add_f32_e32 v52, v106, v52
	v_add_f32_e32 v52, v107, v52
	v_add_f32_e32 v52, v108, v52
	v_add_f32_e32 v76, v109, v52
	v_cvt_pk_bf16_f32 v162, v104, v105
	v_cvt_pk_bf16_f32 v163, v106, v107
	s_waitcnt lgkmcnt(10)
	v_mfma_f32_32x32x16_bf16 v[52:67], v[80:83], v[152:155], v[36:51]
	ds_read_b64_tr_b16 v[68:69], v2 offset:41984
	ds_read_b64_tr_b16 v[70:71], v2 offset:42496
	v_add_f32_e32 v76, v110, v76
	v_add_f32_e32 v76, v111, v76
	v_add_f32_e32 v76, v112, v76
	v_add_f32_e32 v80, v113, v76
	v_cvt_pk_bf16_f32 v156, v108, v109
	v_cvt_pk_bf16_f32 v157, v110, v111
	s_waitcnt lgkmcnt(11)
	v_mfma_f32_32x32x16_bf16 v[116:131], v[164:167], v[144:147], v[116:131]
	ds_read_b64_tr_b16 v[76:77], v2 offset:46080
	ds_read_b64_tr_b16 v[78:79], v2 offset:46592
	v_add_f32_e32 v80, v114, v80
	v_add_f32_e32 v80, v115, v80
	v_add_f32_e32 v80, v84, v80
	v_add_f32_e32 v104, v85, v80
	v_cvt_pk_bf16_f32 v158, v112, v113
	v_cvt_pk_bf16_f32 v159, v114, v115
	s_waitcnt lgkmcnt(12)
	v_mfma_f32_32x32x16_bf16 v[52:67], v[168:171], v[144:147], v[52:67]
	ds_read_b64_tr_b16 v[80:81], v2 offset:43008
	ds_read_b64_tr_b16 v[82:83], v2 offset:43520
	v_add_f32_e32 v104, v86, v104
	v_add_f32_e32 v104, v87, v104
	v_add_f32_e32 v104, v88, v104
	v_add_f32_e32 v108, v89, v104
	v_cvt_pk_bf16_f32 v148, v84, v85
	v_cvt_pk_bf16_f32 v149, v86, v87
	s_waitcnt lgkmcnt(13)
	v_mfma_f32_32x32x16_bf16 v[116:131], v[172:175], v[136:139], v[116:131]
	ds_read_b64_tr_b16 v[104:105], v2 offset:47104
	ds_read_b64_tr_b16 v[106:107], v2 offset:47616
	v_add_f32_e32 v84, v90, v108
	v_add_f32_e32 v84, v91, v84
	v_add_f32_e32 v84, v92, v84
	v_add_f32_e32 v84, v93, v84
	v_cvt_pk_bf16_f32 v150, v88, v89
	v_cvt_pk_bf16_f32 v151, v90, v91
	s_waitcnt lgkmcnt(14)
	v_mfma_f32_32x32x16_bf16 v[52:67], v[176:179], v[136:139], v[52:67]
	ds_read_b64_tr_b16 v[88:89], v2 offset:44032
	ds_read_b64_tr_b16 v[90:91], v2 offset:44544
	v_add_f32_e32 v84, v94, v84
	v_add_f32_e32 v84, v95, v84
	v_add_f32_e32 v84, v96, v84
	v_add_f32_e32 v84, v97, v84
	v_cvt_pk_bf16_f32 v140, v92, v93
	v_cvt_pk_bf16_f32 v141, v94, v95
	s_waitcnt lgkmcnt(14)
	v_mfma_f32_32x32x16_bf16 v[116:131], v[198:201], v[132:135], v[116:131]
	ds_read_b64_tr_b16 v[92:93], v2 offset:48128
	ds_read_b64_tr_b16 v[94:95], v2 offset:48640
	v_mfma_f32_32x32x16_bf16 v[52:67], v[72:75], v[132:135], v[52:67]
	v_add_f32_e32 v72, v98, v84
	v_add_f32_e32 v72, v99, v72
	v_add_f32_e32 v72, 0, v72
	v_cvt_pk_bf16_f32 v142, v96, v97
	v_cvt_pk_bf16_f32 v143, v98, v99
	v_readlane_b32 s22, v254, 60
	v_readlane_b32 s23, v254, 61
	s_mov_b32 s23, s17
	v_add_f32_e32 v191, v191, v72
	v_lshl_add_u64 v[72:73], v[182:183], 0, s[22:23]
	s_mov_b32 s14, m0
	s_mov_b32 m0, s9
	s_nop 0
	global_load_lds_dwordx4 v[72:73], off
	s_mov_b32 m0, s14
	s_add_i32 s9, s13, 0x8000
	v_readlane_b32 s14, v254, 62
	v_readlane_b32 s15, v254, 63
	s_mov_b32 s15, s17
	s_mov_b32 s16, s14
	v_lshl_add_u64 v[72:73], v[180:181], 0, s[14:15]
	s_mov_b32 s14, m0
	s_mov_b32 m0, s9
	s_nop 0
	global_load_lds_dwordx4 v[72:73], off
	s_mov_b32 m0, s14
	v_writelane_b32 v254, s16, 62
	s_nop 1
	v_writelane_b32 v254, s17, 63
	s_waitcnt lgkmcnt(14)
	v_mfma_f32_32x32x16_bf16 v[4:19], v[160:163], v[202:205], v[4:19]
	v_exp_f32_e32 v116, v116
	v_exp_f32_e32 v117, v117
	v_exp_f32_e32 v118, v118
	v_exp_f32_e32 v119, v119
	s_waitcnt lgkmcnt(12)
	v_mfma_f32_32x32x16_bf16 v[20:35], v[160:163], v[100:103], v[20:35]
	v_exp_f32_e32 v120, v120
	v_exp_f32_e32 v121, v121
	v_exp_f32_e32 v122, v122
	v_exp_f32_e32 v123, v123
	ds_read_b128 v[72:75], v189 offset:8192
	ds_read_b128 v[96:99], v189 offset:8704
	s_waitcnt lgkmcnt(12)
	v_mfma_f32_32x32x16_bf16 v[4:19], v[156:159], v[68:71], v[4:19]
	v_exp_f32_e32 v124, v124
	v_exp_f32_e32 v125, v125
	v_exp_f32_e32 v126, v126
	v_exp_f32_e32 v127, v127
	ds_read_b128 v[164:167], v189 offset:10240
	ds_read_b128 v[168:171], v189 offset:10752
	s_waitcnt lgkmcnt(12)
	v_mfma_f32_32x32x16_bf16 v[20:35], v[156:159], v[76:79], v[20:35]
	v_exp_f32_e32 v128, v128
	v_exp_f32_e32 v129, v129
	v_exp_f32_e32 v130, v130
	v_exp_f32_e32 v131, v131
	ds_read_b128 v[172:175], v189 offset:12288
	ds_read_b128 v[176:179], v189 offset:12800
	s_waitcnt lgkmcnt(12)
	v_mfma_f32_32x32x16_bf16 v[4:19], v[148:151], v[80:83], v[4:19]
	v_exp_f32_e32 v52, v52
	v_exp_f32_e32 v53, v53
	v_exp_f32_e32 v54, v54
	v_exp_f32_e32 v55, v55
	ds_read_b128 v[198:201], v189 offset:14336
	ds_read_b128 v[84:87], v189 offset:14848
	s_waitcnt lgkmcnt(12)
	v_mfma_f32_32x32x16_bf16 v[20:35], v[148:151], v[104:107], v[20:35]
	v_exp_f32_e32 v56, v56
	v_exp_f32_e32 v57, v57
	v_exp_f32_e32 v58, v58
	v_exp_f32_e32 v59, v59
	s_waitcnt lgkmcnt(10)
	v_mfma_f32_32x32x16_bf16 v[4:19], v[140:143], v[88:91], v[4:19]
	v_exp_f32_e32 v60, v60
	v_exp_f32_e32 v61, v61
	v_exp_f32_e32 v62, v62
	v_exp_f32_e32 v63, v63
	s_waitcnt lgkmcnt(8)
	v_mfma_f32_32x32x16_bf16 v[20:35], v[140:143], v[92:95], v[20:35]
	v_exp_f32_e32 v64, v64
	v_exp_f32_e32 v65, v65
	v_exp_f32_e32 v66, v66
	v_exp_f32_e32 v67, v67
	s_waitcnt vmcnt(2) lgkmcnt(0)
	s_barrier
; template<int THRL,bool NOMAX> __device__ __forceinline__ void attn_unit(int b,int h,int qb,int t0,const bf16*Q,const bf16*__restrict__ KV,const bf16*__restrict__ GA,bf16*O,char*shm){
;     ...
;   bf16*Ow=O+(rowbase+q0+wid*QBLK)*QP+h*D; const bf16*Gw=GA+(rowbase+q0+wid*QBLK)*GP+h*D;
;   u32x4 gpre[4];
;   #pragma unroll
;   for(int i=0;i<4;++i)gpre[i]=*(const u32x4*)(Gw+(long)(i*8+(lane>>3))*GP+(lane&7)*8);
	s_lshl_b64 s[98:99], s[4:5], 1
	s_add_u32 s98, s84, s98
	s_addc_u32 s99, s85, s99
	s_add_u32 s98, s98, s6
	s_addc_u32 s99, s99, s7
	v_and_b32_e32 v192, 56, v187
	v_lshlrev_b32_e32 v193, 8, v184
	v_lshlrev_b32_e32 v192, 1, v192
	v_and_b32_e32 v193, 0x3800, v193
	v_add_u32_e32 v192, v192, v193
	global_load_dwordx4 v[206:209], v192, s[98:99]
	s_add_u32 s98, s98, 0x4000
	s_addc_u32 s99, s99, 0
	global_load_dwordx4 v[210:213], v192, s[98:99]
	s_add_u32 s98, s98, 0x4000
	s_addc_u32 s99, s99, 0
	global_load_dwordx4 v[214:217], v192, s[98:99]
	s_add_u32 s98, s98, 0x4000
	s_addc_u32 s99, s99, 0
	global_load_dwordx4 v[218:221], v192, s[98:99]
	ds_read_b64_tr_b16 v[88:89], v2 offset:24576
	ds_read_b64_tr_b16 v[90:91], v2 offset:25088
	v_add_f32_e32 v68, v116, v117
	v_add_f32_e32 v68, v118, v68
	v_add_f32_e32 v68, v119, v68
	v_add_f32_e32 v68, v120, v68
	v_add_f32_e32 v68, v121, v68
	v_cvt_pk_bf16_f32 v160, v116, v117
	v_cvt_pk_bf16_f32 v161, v118, v119
	s_waitcnt lgkmcnt(9)
	v_mfma_f32_32x32x16_bf16 v[100:115], v[72:75], v[152:155], v[36:51]
	ds_read_b64_tr_b16 v[92:93], v2 offset:28672
	ds_read_b64_tr_b16 v[94:95], v2 offset:29184
	v_add_f32_e32 v68, v122, v68
	v_add_f32_e32 v68, v123, v68
	v_add_f32_e32 v68, v124, v68
	v_add_f32_e32 v116, v125, v68
	v_cvt_pk_bf16_f32 v162, v120, v121
	v_cvt_pk_bf16_f32 v163, v122, v123
	s_waitcnt lgkmcnt(10)
	v_mfma_f32_32x32x16_bf16 v[68:83], v[96:99], v[152:155], v[36:51]
	ds_read_b64_tr_b16 v[96:97], v2 offset:25600
	ds_read_b64_tr_b16 v[98:99], v2 offset:26112
	v_add_f32_e32 v116, v126, v116
	v_add_f32_e32 v116, v127, v116
	v_add_f32_e32 v116, v128, v116
	v_add_f32_e32 v120, v129, v116
	v_cvt_pk_bf16_f32 v156, v124, v125
	v_cvt_pk_bf16_f32 v157, v126, v127
	s_waitcnt lgkmcnt(11)
	v_mfma_f32_32x32x16_bf16 v[100:115], v[164:167], v[144:147], v[100:115]
	ds_read_b64_tr_b16 v[116:117], v2 offset:29696
	ds_read_b64_tr_b16 v[118:119], v2 offset:30208
	v_add_f32_e32 v120, v130, v120
	v_add_f32_e32 v120, v131, v120
	v_add_f32_e32 v120, v52, v120
	v_add_f32_e32 v124, v53, v120
	v_cvt_pk_bf16_f32 v158, v128, v129
	v_cvt_pk_bf16_f32 v159, v130, v131
	s_waitcnt lgkmcnt(12)
	v_mfma_f32_32x32x16_bf16 v[68:83], v[168:171], v[144:147], v[68:83]
	ds_read_b64_tr_b16 v[120:121], v2 offset:26624
	ds_read_b64_tr_b16 v[122:123], v2 offset:27136
	v_add_f32_e32 v124, v54, v124
	v_add_f32_e32 v124, v55, v124
	v_add_f32_e32 v124, v56, v124
	v_add_f32_e32 v124, v57, v124
	v_cvt_pk_bf16_f32 v148, v52, v53
	v_cvt_pk_bf16_f32 v149, v54, v55
	s_waitcnt lgkmcnt(13)
	v_mfma_f32_32x32x16_bf16 v[100:115], v[172:175], v[136:139], v[100:115]
	ds_read_b64_tr_b16 v[52:53], v2 offset:30720
	ds_read_b64_tr_b16 v[54:55], v2 offset:31232
	v_add_f32_e32 v124, v58, v124
	v_add_f32_e32 v124, v59, v124
	v_add_f32_e32 v124, v60, v124
	v_add_f32_e32 v124, v61, v124
	v_cvt_pk_bf16_f32 v150, v56, v57
	v_cvt_pk_bf16_f32 v151, v58, v59
	s_waitcnt lgkmcnt(14)
	v_mfma_f32_32x32x16_bf16 v[68:83], v[176:179], v[136:139], v[68:83]
	ds_read_b64_tr_b16 v[56:57], v2 offset:27648
	ds_read_b64_tr_b16 v[58:59], v2 offset:28160
	v_add_f32_e32 v124, v62, v124
	v_add_f32_e32 v124, v63, v124
	v_add_f32_e32 v124, v64, v124
	v_add_f32_e32 v124, v65, v124
	v_cvt_pk_bf16_f32 v140, v60, v61
	v_cvt_pk_bf16_f32 v141, v62, v63
	s_waitcnt lgkmcnt(14)
	v_mfma_f32_32x32x16_bf16 v[100:115], v[198:201], v[132:135], v[100:115]
	ds_read_b64_tr_b16 v[60:61], v2 offset:31744
	ds_read_b64_tr_b16 v[62:63], v2 offset:32256
	v_mfma_f32_32x32x16_bf16 v[68:83], v[84:87], v[132:135], v[68:83]
	v_add_f32_e32 v84, v66, v124
	v_add_f32_e32 v84, v67, v84
	v_add_f32_e32 v84, 0, v84
	v_cvt_pk_bf16_f32 v142, v64, v65
	v_cvt_pk_bf16_f32 v143, v66, v67
	s_mov_b32 s14, s20
	v_lshl_add_u64 v[64:65], v[180:181], 0, s[20:21]
	s_add_i32 s13, s13, 0xa000
	s_mov_b32 s9, m0
	s_mov_b32 m0, s13
	s_nop 0
	global_load_lds_dwordx4 v[64:65], off
	s_mov_b32 m0, s9
	v_writelane_b32 v254, s14, 56
	v_add_f32_e32 v182, v191, v84
	s_nop 0
	v_writelane_b32 v254, s15, 57
	s_waitcnt lgkmcnt(14)
	v_mfma_f32_32x32x16_bf16 v[4:19], v[160:163], v[88:91], v[4:19]
	v_exp_f32_e32 v100, v100
	v_exp_f32_e32 v101, v101
	v_exp_f32_e32 v102, v102
	v_exp_f32_e32 v103, v103
	s_waitcnt lgkmcnt(12)
	v_mfma_f32_32x32x16_bf16 v[20:35], v[160:163], v[92:95], v[20:35]
	v_exp_f32_e32 v104, v104
	v_exp_f32_e32 v105, v105
	v_exp_f32_e32 v106, v106
	v_exp_f32_e32 v107, v107
	ds_read_b128 v[64:67], v189 offset:16384
	ds_read_b128 v[124:127], v189 offset:16896
	s_waitcnt lgkmcnt(12)
	v_mfma_f32_32x32x16_bf16 v[4:19], v[156:159], v[96:99], v[4:19]
	v_exp_f32_e32 v108, v108
	v_exp_f32_e32 v109, v109
	v_exp_f32_e32 v110, v110
	v_exp_f32_e32 v111, v111
	ds_read_b128 v[128:131], v189 offset:18432
	ds_read_b128 v[164:167], v189 offset:18944
	s_waitcnt lgkmcnt(12)
	v_mfma_f32_32x32x16_bf16 v[20:35], v[156:159], v[116:119], v[20:35]
	v_exp_f32_e32 v112, v112
	v_exp_f32_e32 v113, v113
	v_exp_f32_e32 v114, v114
	v_exp_f32_e32 v115, v115
	ds_read_b128 v[168:171], v189 offset:20480
	ds_read_b128 v[172:175], v189 offset:20992
	s_waitcnt lgkmcnt(12)
	v_mfma_f32_32x32x16_bf16 v[4:19], v[148:151], v[120:123], v[4:19]
	v_exp_f32_e32 v68, v68
	v_exp_f32_e32 v69, v69
	v_exp_f32_e32 v70, v70
	v_exp_f32_e32 v71, v71
	ds_read_b128 v[120:123], v189 offset:22528
	ds_read_b128 v[116:119], v189 offset:23040
	s_waitcnt lgkmcnt(12)
	v_mfma_f32_32x32x16_bf16 v[20:35], v[148:151], v[52:55], v[20:35]
	v_exp_f32_e32 v72, v72
	v_exp_f32_e32 v73, v73
	v_exp_f32_e32 v74, v74
	v_exp_f32_e32 v75, v75
	s_waitcnt lgkmcnt(10)
	v_mfma_f32_32x32x16_bf16 v[4:19], v[140:143], v[56:59], v[4:19]
	v_exp_f32_e32 v76, v76
	v_exp_f32_e32 v77, v77
	v_exp_f32_e32 v78, v78
	v_exp_f32_e32 v79, v79
	s_waitcnt lgkmcnt(8)
	v_mfma_f32_32x32x16_bf16 v[20:35], v[140:143], v[60:63], v[20:35]
	v_exp_f32_e32 v80, v80
	v_exp_f32_e32 v81, v81
	v_exp_f32_e32 v82, v82
	v_exp_f32_e32 v83, v83
	s_waitcnt vmcnt(5) lgkmcnt(0)
	s_barrier
;   #define RESC() do{ if(resc){ asm volatile("s_waitcnt lgkmcnt(0)":::"memory"); \
;       _Pragma("unroll") for(int d_=0;d_<2;++d_) _Pragma("unroll") for(int r=0;r<16;++r)o[d_][r]*=wsf[crow(r,hi)]; } }while(0)
;   #define ROT() do{sl_prev=sl_cur;sl_cur=sl_next;sl_next=(sl_next==(NSLOT-1)*SLOTB)?0:sl_next+SLOTB;}while(0)
;   #define ENDW(tt) do{ if((tt)+3<NT){WAIT_BAR(2);} else if((tt)+2<NT){WAIT_BAR(1);} else {WAIT_BAR(0);} }while(0)
; template<int THRL,bool NOMAX> __device__ __forceinline__ void attn_unit(int b,int h,int qb,int t0,const bf16*Q,const bf16*__restrict__ KV,const bf16*__restrict__ GA,bf16*O,char*shm){
;     ...
;   for(;t+1<NT;t+=2){
;     STEP(pB0,pB1,pA0,pA1,t,(t+3<NT),(t+1<NT),(t+1<NT));       ENDW(t);   RESC(); ROT();
;     STEP(pA0,pA1,pB0,pB1,t+1,(t+4<NT),(t+2<NT),(t+2<NT));     ENDW(t+1); RESC(); ROT();
	ds_read_b64_tr_b16 v[176:177], v2 offset:32768
	ds_read_b64_tr_b16 v[178:179], v2 offset:33280
	v_add_f32_e32 v52, v100, v101
	v_add_f32_e32 v52, v102, v52
	v_add_f32_e32 v52, v103, v52
	v_add_f32_e32 v52, v104, v52
	v_add_f32_e32 v52, v105, v52
	v_cvt_pk_bf16_f32 v160, v100, v101
	v_cvt_pk_bf16_f32 v161, v102, v103
	s_waitcnt lgkmcnt(9)
	v_mfma_f32_32x32x16_bf16 v[84:99], v[64:67], v[152:155], v[36:51]
	ds_read_b64_tr_b16 v[100:101], v2 offset:36864
	ds_read_b64_tr_b16 v[102:103], v2 offset:37376
	v_add_f32_e32 v52, v106, v52
	v_add_f32_e32 v52, v107, v52
	v_add_f32_e32 v52, v108, v52
	v_add_f32_e32 v140, v109, v52
	v_cvt_pk_bf16_f32 v162, v104, v105
	v_cvt_pk_bf16_f32 v163, v106, v107
	s_waitcnt lgkmcnt(10)
	v_mfma_f32_32x32x16_bf16 v[52:67], v[124:127], v[152:155], v[36:51]
	ds_read_b64_tr_b16 v[124:125], v2 offset:33792
	ds_read_b64_tr_b16 v[126:127], v2 offset:34304
	v_add_f32_e32 v104, v110, v140
	v_add_f32_e32 v104, v111, v104
	v_add_f32_e32 v104, v112, v104
	v_add_f32_e32 v104, v113, v104
	v_cvt_pk_bf16_f32 v156, v108, v109
	v_cvt_pk_bf16_f32 v157, v110, v111
	s_waitcnt lgkmcnt(11)
	v_mfma_f32_32x32x16_bf16 v[84:99], v[128:131], v[144:147], v[84:99]
	ds_read_b64_tr_b16 v[106:107], v2 offset:37888
	ds_read_b64_tr_b16 v[108:109], v2 offset:38400
	v_add_f32_e32 v104, v114, v104
	v_add_f32_e32 v104, v115, v104
	v_add_f32_e32 v104, v68, v104
	v_add_f32_e32 v104, v69, v104
	v_cvt_pk_bf16_f32 v158, v112, v113
	v_cvt_pk_bf16_f32 v159, v114, v115
	s_waitcnt lgkmcnt(12)
	v_mfma_f32_32x32x16_bf16 v[52:67], v[164:167], v[144:147], v[52:67]
	ds_read_b64_tr_b16 v[110:111], v2 offset:34816
	ds_read_b64_tr_b16 v[112:113], v2 offset:35328
	v_add_f32_e32 v104, v70, v104
	v_add_f32_e32 v104, v71, v104
	v_add_f32_e32 v104, v72, v104
	v_add_f32_e32 v104, v73, v104
	v_cvt_pk_bf16_f32 v148, v68, v69
	v_cvt_pk_bf16_f32 v149, v70, v71
	s_waitcnt lgkmcnt(13)
	v_mfma_f32_32x32x16_bf16 v[84:99], v[168:171], v[136:139], v[84:99]
	ds_read_b64_tr_b16 v[68:69], v2 offset:38912
	ds_read_b64_tr_b16 v[70:71], v2 offset:39424
	v_add_f32_e32 v104, v74, v104
	v_add_f32_e32 v104, v75, v104
	v_add_f32_e32 v104, v76, v104
	v_add_f32_e32 v104, v77, v104
	v_cvt_pk_bf16_f32 v150, v72, v73
	v_cvt_pk_bf16_f32 v151, v74, v75
	s_waitcnt lgkmcnt(14)
	v_mfma_f32_32x32x16_bf16 v[52:67], v[172:175], v[136:139], v[52:67]
	ds_read_b64_tr_b16 v[72:73], v2 offset:35840
	ds_read_b64_tr_b16 v[74:75], v2 offset:36352
	v_add_f32_e32 v104, v78, v104
	v_add_f32_e32 v104, v79, v104
	v_add_f32_e32 v104, v80, v104
	v_add_f32_e32 v104, v81, v104
	v_cvt_pk_bf16_f32 v140, v76, v77
	v_cvt_pk_bf16_f32 v141, v78, v79
	s_waitcnt lgkmcnt(14)
	v_mfma_f32_32x32x16_bf16 v[84:99], v[120:123], v[132:135], v[84:99]
	ds_read_b64_tr_b16 v[76:77], v2 offset:39936
	ds_read_b64_tr_b16 v[78:79], v2 offset:40448
	v_add_f32_e32 v104, v82, v104
	v_add_f32_e32 v104, v83, v104
	v_add_f32_e32 v104, 0, v104
	v_cvt_pk_bf16_f32 v142, v80, v81
	v_cvt_pk_bf16_f32 v143, v82, v83
	v_mfma_f32_32x32x16_bf16 v[52:67], v[116:119], v[132:135], v[52:67]
	s_mov_b32 s14, s22
	v_lshl_add_u64 v[80:81], v[180:181], 0, s[22:23]
	s_mov_b32 s9, m0
	s_mov_b32 m0, s8
	s_nop 0
	global_load_lds_dwordx4 v[80:81], off
	s_mov_b32 m0, s9
	v_writelane_b32 v254, s14, 60
	v_add_f32_e32 v104, v182, v104
	s_nop 0
	v_writelane_b32 v254, s15, 61
	s_waitcnt lgkmcnt(14)
	v_mfma_f32_32x32x16_bf16 v[4:19], v[160:163], v[176:179], v[4:19]
	v_exp_f32_e32 v84, v84
	v_exp_f32_e32 v85, v85
	v_exp_f32_e32 v86, v86
	v_exp_f32_e32 v87, v87
	s_waitcnt lgkmcnt(12)
	v_mfma_f32_32x32x16_bf16 v[20:35], v[160:163], v[100:103], v[20:35]
	v_exp_f32_e32 v88, v88
	v_exp_f32_e32 v89, v89
	v_exp_f32_e32 v90, v90
	v_exp_f32_e32 v91, v91
	ds_read_b128 v[114:117], v189
	ds_read_b128 v[118:121], v189 offset:512
	s_waitcnt lgkmcnt(12)
	v_mfma_f32_32x32x16_bf16 v[4:19], v[156:159], v[124:127], v[4:19]
	v_exp_f32_e32 v92, v92
	v_exp_f32_e32 v93, v93
	v_exp_f32_e32 v94, v94
	v_exp_f32_e32 v95, v95
	ds_read_b128 v[122:125], v189 offset:2048
	ds_read_b128 v[126:129], v189 offset:2560
	s_waitcnt lgkmcnt(12)
	v_mfma_f32_32x32x16_bf16 v[20:35], v[156:159], v[106:109], v[20:35]
	v_exp_f32_e32 v96, v96
	v_exp_f32_e32 v97, v97
	v_exp_f32_e32 v98, v98
	v_exp_f32_e32 v99, v99
	ds_read_b128 v[106:109], v189 offset:4096
	ds_read_b128 v[164:167], v189 offset:4608
	s_waitcnt lgkmcnt(12)
	v_mfma_f32_32x32x16_bf16 v[4:19], v[148:151], v[110:113], v[4:19]
	v_exp_f32_e32 v52, v52
	v_exp_f32_e32 v53, v53
	v_exp_f32_e32 v54, v54
	v_exp_f32_e32 v55, v55
	ds_read_b128 v[110:113], v189 offset:6144
	ds_read_b128 v[100:103], v189 offset:6656
	s_waitcnt lgkmcnt(12)
	v_mfma_f32_32x32x16_bf16 v[20:35], v[148:151], v[68:71], v[20:35]
	v_exp_f32_e32 v56, v56
	v_exp_f32_e32 v57, v57
	v_exp_f32_e32 v58, v58
	v_exp_f32_e32 v59, v59
	s_waitcnt lgkmcnt(10)
	v_mfma_f32_32x32x16_bf16 v[4:19], v[140:143], v[72:75], v[4:19]
	v_exp_f32_e32 v60, v60
	v_exp_f32_e32 v61, v61
	v_exp_f32_e32 v62, v62
	v_exp_f32_e32 v63, v63
	s_waitcnt lgkmcnt(8)
	v_mfma_f32_32x32x16_bf16 v[20:35], v[140:143], v[76:79], v[20:35]
	v_exp_f32_e32 v64, v64
	v_exp_f32_e32 v65, v65
	v_exp_f32_e32 v66, v66
	v_exp_f32_e32 v67, v67
	s_waitcnt vmcnt(0) lgkmcnt(0)
	s_barrier
;   #define RESC() do{ if(resc){ asm volatile("s_waitcnt lgkmcnt(0)":::"memory"); \
;       _Pragma("unroll") for(int d_=0;d_<2;++d_) _Pragma("unroll") for(int r=0;r<16;++r)o[d_][r]*=wsf[crow(r,hi)]; } }while(0)
; template<int THRL,bool NOMAX> __device__ __forceinline__ void attn_unit(int b,int h,int qb,int t0,const bf16*Q,const bf16*__restrict__ KV,const bf16*__restrict__ GA,bf16*O,char*shm){
;     ...
;   STEP(pB0,pB1,pA0,pA1,NT-1,false,false,false); RESC();
	ds_read_b64_tr_b16 v[168:169], v2 offset:40960
	ds_read_b64_tr_b16 v[170:171], v2 offset:41472
	v_add_f32_e32 v68, v84, v85
	v_add_f32_e32 v68, v86, v68
	v_add_f32_e32 v68, v87, v68
	v_add_f32_e32 v68, v88, v68
	v_add_f32_e32 v105, v89, v68
	v_cvt_pk_bf16_f32 v160, v84, v85
	v_cvt_pk_bf16_f32 v161, v86, v87
	s_waitcnt lgkmcnt(9)
	v_mfma_f32_32x32x16_bf16 v[68:83], v[114:117], v[152:155], v[36:51]
	ds_read_b64_tr_b16 v[84:85], v2 offset:45056
	ds_read_b64_tr_b16 v[86:87], v2 offset:45568
	s_waitcnt lgkmcnt(10)
	v_mfma_f32_32x32x16_bf16 v[36:51], v[118:121], v[152:155], v[36:51]
	v_add_f32_e32 v105, v90, v105
	v_add_f32_e32 v105, v91, v105
	v_add_f32_e32 v105, v92, v105
	v_add_f32_e32 v105, v93, v105
	v_cvt_pk_bf16_f32 v162, v88, v89
	v_cvt_pk_bf16_f32 v163, v90, v91
	ds_read_b64_tr_b16 v[88:89], v2 offset:41984
	ds_read_b64_tr_b16 v[90:91], v2 offset:42496
	v_add_f32_e32 v105, v94, v105
	v_add_f32_e32 v105, v95, v105
	v_add_f32_e32 v105, v96, v105
	v_add_f32_e32 v105, v97, v105
	v_cvt_pk_bf16_f32 v156, v92, v93
	v_cvt_pk_bf16_f32 v157, v94, v95
	s_waitcnt lgkmcnt(11)
	v_mfma_f32_32x32x16_bf16 v[68:83], v[122:125], v[144:147], v[68:83]
	ds_read_b64_tr_b16 v[92:93], v2 offset:46080
	ds_read_b64_tr_b16 v[94:95], v2 offset:46592
	s_waitcnt lgkmcnt(12)
	v_mfma_f32_32x32x16_bf16 v[36:51], v[126:129], v[144:147], v[36:51]
	v_add_f32_e32 v105, v98, v105
	v_add_f32_e32 v105, v99, v105
	v_add_f32_e32 v105, v52, v105
	v_add_f32_e32 v105, v53, v105
	v_cvt_pk_bf16_f32 v158, v96, v97
	v_cvt_pk_bf16_f32 v159, v98, v99
	ds_read_b64_tr_b16 v[96:97], v2 offset:43008
	ds_read_b64_tr_b16 v[98:99], v2 offset:43520
	v_add_f32_e32 v105, v54, v105
	v_add_f32_e32 v105, v55, v105
	v_add_f32_e32 v105, v56, v105
	v_add_f32_e32 v105, v57, v105
	v_cvt_pk_bf16_f32 v148, v52, v53
	v_cvt_pk_bf16_f32 v149, v54, v55
	s_waitcnt lgkmcnt(13)
	v_mfma_f32_32x32x16_bf16 v[68:83], v[106:109], v[136:139], v[68:83]
	ds_read_b64_tr_b16 v[52:53], v2 offset:47104
	ds_read_b64_tr_b16 v[54:55], v2 offset:47616
	s_waitcnt lgkmcnt(14)
	v_mfma_f32_32x32x16_bf16 v[36:51], v[164:167], v[136:139], v[36:51]
	v_add_f32_e32 v105, v58, v105
	v_add_f32_e32 v105, v59, v105
	v_add_f32_e32 v105, v60, v105
	v_add_f32_e32 v105, v61, v105
	v_cvt_pk_bf16_f32 v150, v56, v57
	v_cvt_pk_bf16_f32 v151, v58, v59
	ds_read_b64_tr_b16 v[56:57], v2 offset:44032
	ds_read_b64_tr_b16 v[58:59], v2 offset:44544
	v_add_f32_e32 v105, v62, v105
	v_add_f32_e32 v105, v63, v105
	v_add_f32_e32 v105, v64, v105
	v_add_f32_e32 v105, v65, v105
	v_cvt_pk_bf16_f32 v140, v60, v61
	v_cvt_pk_bf16_f32 v141, v62, v63
	s_waitcnt lgkmcnt(14)
	v_mfma_f32_32x32x16_bf16 v[68:83], v[110:113], v[132:135], v[68:83]
	ds_read_b64_tr_b16 v[60:61], v2 offset:48128
	ds_read_b64_tr_b16 v[62:63], v2 offset:48640
	v_mfma_f32_32x32x16_bf16 v[36:51], v[100:103], v[132:135], v[36:51]
	v_add_f32_e32 v2, v66, v105
	v_add_f32_e32 v2, v67, v2
	v_add_f32_e32 v2, 0, v2
	v_cvt_pk_bf16_f32 v142, v64, v65
	v_cvt_pk_bf16_f32 v143, v66, v67
	s_waitcnt lgkmcnt(14)
	v_mfma_f32_32x32x16_bf16 v[4:19], v[160:163], v[168:171], v[4:19]
	s_nop 1
	v_exp_f32_e32 v68, v68
	v_exp_f32_e32 v69, v69
	v_exp_f32_e32 v70, v70
	v_exp_f32_e32 v71, v71
	s_waitcnt lgkmcnt(12)
	v_mfma_f32_32x32x16_bf16 v[20:35], v[160:163], v[84:87], v[20:35]
	v_exp_f32_e32 v72, v72
	v_exp_f32_e32 v73, v73
	v_exp_f32_e32 v74, v74
	v_exp_f32_e32 v75, v75
	s_waitcnt lgkmcnt(10)
	v_mfma_f32_32x32x16_bf16 v[4:19], v[156:159], v[88:91], v[4:19]
	v_exp_f32_e32 v76, v76
	v_exp_f32_e32 v77, v77
	v_exp_f32_e32 v78, v78
	v_exp_f32_e32 v79, v79
	s_waitcnt lgkmcnt(8)
	v_mfma_f32_32x32x16_bf16 v[20:35], v[156:159], v[92:95], v[20:35]
	v_exp_f32_e32 v80, v80
	v_exp_f32_e32 v81, v81
	v_exp_f32_e32 v82, v82
	v_exp_f32_e32 v83, v83
	s_waitcnt lgkmcnt(6)
; #define SBAR() __builtin_amdgcn_sched_barrier(0)
;   #define RESC() do{ if(resc){ asm volatile("s_waitcnt lgkmcnt(0)":::"memory"); \
;       _Pragma("unroll") for(int d_=0;d_<2;++d_) _Pragma("unroll") for(int r=0;r<16;++r)o[d_][r]*=wsf[crow(r,hi)]; } }while(0)
;   #define PKW(P,B) cvtpk_s(P[B],P[B+1])
; template<int THRL,bool NOMAX> __device__ __forceinline__ void attn_unit(int b,int h,int qb,int t0,const bf16*Q,const bf16*__restrict__ KV,const bf16*__restrict__ GA,bf16*O,char*shm){
;     ...
;   STEP(pB0,pB1,pA0,pA1,NT-1,false,false,false); RESC();
;   { float sacc=pB0[0]+pB0[1]; _Pragma("unroll") for(int r=2;r<16;++r)sacc+=pB0[r]; _Pragma("unroll") for(int r=0;r<16;++r)sacc+=pB1[r]; l_reg+=sacc;
;     pw0=(u32x4){PKW(pB0,0),PKW(pB0,2),PKW(pB0,4),PKW(pB0,6)};pw1=(u32x4){PKW(pB0,8),PKW(pB0,10),PKW(pB0,12),PKW(pB0,14)};pw2=(u32x4){PKW(pB1,0),PKW(pB1,2),PKW(pB1,4),PKW(pB1,6)};pw3=(u32x4){PKW(pB1,8),PKW(pB1,10),PKW(pB1,12),PKW(pB1,14)};
;     SBAR(); pv(o,vb0+sl_cur,PAF(0),PAF(1),PAF(2),PAF(3)); }
;     ...
;   {auto rr=__builtin_amdgcn_permlane32_swap(__float_as_uint(l_reg),__float_as_uint(l_reg),false,false);l_reg=__uint_as_float(rr[0])+__uint_as_float(rr[1]);}
;   if(hi==0)wsf[32+r32]=l_reg;asm volatile("s_waitcnt lgkmcnt(0)":::"memory");
	v_mfma_f32_32x32x16_bf16 v[4:19], v[148:151], v[96:99], v[4:19]
	v_exp_f32_e32 v36, v36
	v_exp_f32_e32 v37, v37
	v_exp_f32_e32 v38, v38
	v_exp_f32_e32 v39, v39
	s_waitcnt lgkmcnt(4)
	v_mfma_f32_32x32x16_bf16 v[20:35], v[148:151], v[52:55], v[20:35]
	v_exp_f32_e32 v40, v40
	v_exp_f32_e32 v41, v41
	v_exp_f32_e32 v42, v42
	v_exp_f32_e32 v43, v43
	s_waitcnt lgkmcnt(2)
	v_mfma_f32_32x32x16_bf16 v[4:19], v[140:143], v[56:59], v[4:19]
	v_exp_f32_e32 v44, v44
	v_exp_f32_e32 v45, v45
	v_exp_f32_e32 v46, v46
	v_exp_f32_e32 v47, v47
	s_waitcnt lgkmcnt(0)
	v_mfma_f32_32x32x16_bf16 v[20:35], v[140:143], v[60:63], v[20:35]
	v_exp_f32_e32 v48, v48
	v_exp_f32_e32 v49, v49
	v_exp_f32_e32 v50, v50
	v_exp_f32_e32 v51, v51
	v_add_f32_e32 v52, v68, v69
	v_add_f32_e32 v52, v70, v52
	v_add_f32_e32 v52, v71, v52
	v_add_f32_e32 v52, v72, v52
	v_add_f32_e32 v52, v73, v52
	v_add_f32_e32 v52, v74, v52
	v_add_f32_e32 v52, v75, v52
	v_add_f32_e32 v52, v76, v52
	v_add_f32_e32 v52, v77, v52
	v_add_f32_e32 v52, v78, v52
	v_add_f32_e32 v52, v79, v52
	v_add_f32_e32 v52, v80, v52
	v_add_f32_e32 v52, v81, v52
	v_add_f32_e32 v52, v82, v52
	v_add_f32_e32 v52, v83, v52
	v_add_f32_e32 v52, v36, v52
	v_add_f32_e32 v52, v37, v52
	v_add_f32_e32 v52, v38, v52
	v_add_f32_e32 v52, v39, v52
	v_add_f32_e32 v52, v40, v52
	v_add_f32_e32 v52, v41, v52
	v_add_f32_e32 v52, v42, v52
	v_add_f32_e32 v52, v43, v52
	v_add_f32_e32 v52, v44, v52
	v_add_f32_e32 v52, v45, v52
	v_add_f32_e32 v52, v46, v52
	v_add_f32_e32 v52, v47, v52
	v_add_f32_e32 v52, v48, v52
	v_add_f32_e32 v52, v49, v52
	v_add_f32_e32 v52, v50, v52
	v_add_f32_e32 v52, v51, v52
	v_add_f32_e32 v2, v104, v2
	v_add_f32_e32 v2, v2, v52
	v_cvt_pk_bf16_f32 v36, v36, v37
	v_cvt_pk_bf16_f32 v52, v68, v69
	v_cvt_pk_bf16_f32 v53, v70, v71
	v_cvt_pk_bf16_f32 v54, v72, v73
	v_cvt_pk_bf16_f32 v55, v74, v75
	v_cvt_pk_bf16_f32 v56, v76, v77
	v_cvt_pk_bf16_f32 v57, v78, v79
	v_cvt_pk_bf16_f32 v58, v80, v81
	v_cvt_pk_bf16_f32 v59, v82, v83
	v_cvt_pk_bf16_f32 v37, v38, v39
	v_cvt_pk_bf16_f32 v38, v40, v41
	v_cvt_pk_bf16_f32 v39, v42, v43
	v_cvt_pk_bf16_f32 v40, v44, v45
	v_cvt_pk_bf16_f32 v41, v46, v47
	v_cvt_pk_bf16_f32 v42, v48, v49
	v_cvt_pk_bf16_f32 v43, v50, v51
	ds_read_b64_tr_b16 v[44:45],v190 offset:0
	ds_read_b64_tr_b16 v[46:47],v190 offset:512
	ds_read_b64_tr_b16 v[48:49],v190 offset:1024
	ds_read_b64_tr_b16 v[50:51],v190 offset:1536
	ds_read_b64_tr_b16 v[60:61],v190 offset:2048
	ds_read_b64_tr_b16 v[62:63],v190 offset:2560
	ds_read_b64_tr_b16 v[64:65],v190 offset:3072
	ds_read_b64_tr_b16 v[66:67],v190 offset:3584
	s_waitcnt lgkmcnt(0)
	s_nop 0
	v_mfma_f32_32x32x16_bf16 v[4:19], v[52:55], v[44:47], v[4:19]
	ds_read_b64_tr_b16 v[44:45],v190 offset:4096
	ds_read_b64_tr_b16 v[46:47],v190 offset:4608
	v_mfma_f32_32x32x16_bf16 v[4:19], v[56:59], v[48:51], v[4:19]
	ds_read_b64_tr_b16 v[48:49],v190 offset:5120
	ds_read_b64_tr_b16 v[50:51],v190 offset:5632
	v_mfma_f32_32x32x16_bf16 v[4:19], v[36:39], v[60:63], v[4:19]
	ds_read_b64_tr_b16 v[60:61],v190 offset:6144
	ds_read_b64_tr_b16 v[62:63],v190 offset:6656
	v_mfma_f32_32x32x16_bf16 v[4:19], v[40:43], v[64:67], v[4:19]
	ds_read_b64_tr_b16 v[64:65],v190 offset:7168
	ds_read_b64_tr_b16 v[66:67],v190 offset:7680
	s_waitcnt lgkmcnt(0)
	v_mfma_f32_32x32x16_bf16 v[20:35], v[52:55], v[44:47], v[20:35]
	v_cmp_gt_u32_e32 vcc, 32, v184
	v_mfma_f32_32x32x16_bf16 v[20:35], v[56:59], v[48:51], v[20:35]
	v_mfma_f32_32x32x16_bf16 v[20:35], v[36:39], v[60:63], v[20:35]
	v_mov_b32_e32 v36, v2
	s_nop 1
	v_permlane32_swap_b32_e32 v2, v36
	v_mfma_f32_32x32x16_bf16 v[20:35], v[40:43], v[64:67], v[20:35]
	s_and_saveexec_b64 s[8:9], vcc
	s_cbranch_execz .LBB0_470
	v_lshl_add_u32 v37, v185, 2, s12
	v_add_f32_e32 v2, v2, v36
	ds_write_b32 v37, v2 offset:49280
	s_branch .LBB0_470
